# grid barrier GEMM1->summary: L2 write-back dropped (all data crossing it is write-through; weight copies are flushed by the next barrier)
# speedup vs baseline: 1.0054x; 1.0051x over previous
.LBB0_370:
	s_andn2_saveexec_b64 s[6:7], s[6:7]
	s_cbranch_execz .LBB0_390
	s_mov_b64 s[6:7], exec
	s_waitcnt vmcnt(0) lgkmcnt(0)
	s_waitcnt vmcnt(0)
	v_mbcnt_lo_u32_b32 v1, s6, 0
	v_mbcnt_hi_u32_b32 v1, s7, v1
	v_cmp_eq_u32_e32 vcc, 0, v1
	s_and_saveexec_b64 s[22:23], vcc
	s_cbranch_execz .LBB0_373
	s_bcnt1_i32_b64 s6, s[6:7]
	v_mov_b32_e32 v2, s6
	v_readlane_b32 s6, v253, 21
	v_readlane_b32 s7, v253, 22
	s_nop 4
	global_atomic_add v2, v149, v2, s[6:7] sc0
